# split-K partial loads of phase 3 non-temporal (read once)
# baseline (speedup 1.0000x reference)
; #define LAS __attribute__((address_space(3)))
; __device__ __forceinline__ void phase3(const Args& a, LAS unsigned char* lds) {
;     ...
;     for (int item = blockIdx.x; item < nchunk; item += gridDim.x) {
;         const int kv = (item * 32) >> 12;
;         __syncthreads();
;         { const f32x4* src = (const f32x4*)(a.in[7] + (size_t)kv * 256 * 64);
; #pragma unroll
;           for (int i = 0; i < 8; ++i) ((LAS f32x4*)w2s)[tid + 512 * i] = src[tid + 512 * i]; }
;         if (tid < 256) { float t = 0.f;
; #pragma unroll
;             for (int kch = 0; kch < 64; ++kch) t += c1p[kch * 512 + kv * 256 + tid];
;             c1s[tid] = t; }
;         __syncthreads();
; #pragma unroll 1
;         for (int rr = 0; rr < 4; ++rr) {
;             const int R = item * 32 + wave * 4 + rr, bh = (R >> 7) & 31, n = R & 127;
;             f32x4 h4 = *(const LAS f32x4*)(c1s + 4 * lane);
; #pragma unroll
;             for (int kc = 0; kc < 4; ++kc) h4 += *(const f32x4*)(part + ((size_t)kc * 8192 + R) * 256 + 4 * lane);
.LBB0_589:
	s_ashr_i32 s4, s20, 7
	s_ashr_i32 s5, s4, 31
	s_lshl_b64 s[0:1], s[4:5], 16
	s_add_u32 s0, s86, s0
	s_addc_u32 s1, s87, s1
	v_lshl_add_u64 v[10:11], s[0:1], 0, v[8:9]
	v_add_co_u32_e32 v36, vcc, s14, v10
	s_waitcnt vmcnt(0) lgkmcnt(0)
	s_nop 0
	v_addc_co_u32_e32 v37, vcc, 0, v11, vcc
	v_add_co_u32_e32 v44, vcc, s15, v10
	s_barrier
	v_lshl_add_u32 v168, s20, 5, v13
	v_mov_b32_e32 v169, 0
	v_lshlrev_b64 v[168:169], 10, v[168:169]
	v_lshl_add_u64 v[168:169], v[4:5], 0, v[168:169]
	s_mov_b32 s6, 0x800000
	s_mov_b32 s7, 0
	v_lshl_add_u64 v[170:171], v[168:169], 0, s[6:7]
	v_lshl_add_u64 v[172:173], v[170:171], 0, s[6:7]
	v_lshl_add_u64 v[174:175], v[172:173], 0, s[6:7]
	global_load_dwordx4 v[100:103], v[168:169], off nt
	global_load_dwordx4 v[104:107], v[170:171], off nt
	global_load_dwordx4 v[108:111], v[172:173], off nt
	global_load_dwordx4 v[112:115], v[174:175], off nt
	global_load_dwordx4 v[116:119], v[168:169], off offset:1024 nt
	global_load_dwordx4 v[120:123], v[170:171], off offset:1024 nt
	global_load_dwordx4 v[124:127], v[172:173], off offset:1024 nt
	global_load_dwordx4 v[128:131], v[174:175], off offset:1024 nt
	global_load_dwordx4 v[132:135], v[168:169], off offset:2048 nt
	global_load_dwordx4 v[136:139], v[170:171], off offset:2048 nt
	global_load_dwordx4 v[140:143], v[172:173], off offset:2048 nt
	global_load_dwordx4 v[144:147], v[174:175], off offset:2048 nt
	global_load_dwordx4 v[152:155], v[168:169], off offset:3072 nt
	global_load_dwordx4 v[156:159], v[170:171], off offset:3072 nt
	global_load_dwordx4 v[160:163], v[172:173], off offset:3072 nt
	global_load_dwordx4 v[164:167], v[174:175], off offset:3072 nt
	global_load_dword v176, v[6:7], off
	s_nop 0
	v_addc_co_u32_e32 v45, vcc, 0, v11, vcc
	v_add_co_u32_e32 v52, vcc, 0xa000, v10
	s_nop 1
	v_addc_co_u32_e32 v53, vcc, 0, v11, vcc
	global_load_dwordx4 v[24:27], v8, s[0:1]
	global_load_dwordx4 v[28:31], v[36:37], off
	global_load_dwordx4 v[32:35], v1, s[0:1]
	s_nop 0
	global_load_dwordx4 v[36:39], v[44:45], off
	global_load_dwordx4 v[40:43], v19, s[0:1]
	s_nop 0
	global_load_dwordx4 v[44:47], v[52:53], off
	global_load_dwordx4 v[48:51], v20, s[0:1]
	v_add_co_u32_e32 v10, vcc, 0xe000, v10
	s_nop 1
	v_addc_co_u32_e32 v11, vcc, 0, v11, vcc
	global_load_dwordx4 v[52:55], v[10:11], off
	s_waitcnt vmcnt(7)
	ds_write_b128 v18, v[24:27]
	s_waitcnt vmcnt(6)
	ds_write_b128 v18, v[28:31] offset:8192
	s_waitcnt vmcnt(5)
	ds_write_b128 v18, v[32:35] offset:16384
	s_waitcnt vmcnt(4)
	ds_write_b128 v18, v[36:39] offset:24576
	s_waitcnt vmcnt(3)
	ds_write_b128 v18, v[40:43] offset:32768
	s_waitcnt vmcnt(2)
	ds_write_b128 v18, v[44:47] offset:40960
	s_waitcnt vmcnt(1)
	ds_write_b128 v18, v[48:51] offset:49152
	s_waitcnt vmcnt(0)
	ds_write_b128 v18, v[52:55] offset:57344
	s_and_saveexec_b64 s[0:1], s[2:3]
	s_cbranch_execz .LBB0_591
	v_lshl_or_b32 v10, s4, 8, v184
	v_add_u32_e32 v24, 0x200, v10
	v_ashrrev_i32_e32 v25, 31, v24
	v_lshl_add_u64 v[32:33], v[24:25], 2, s[10:11]
	v_add_u32_e32 v24, 0x400, v10
	v_ashrrev_i32_e32 v25, 31, v24
	v_lshl_add_u64 v[34:35], v[24:25], 2, s[10:11]
	v_add_u32_e32 v24, 0x600, v10
	v_ashrrev_i32_e32 v25, 31, v24
	v_lshl_add_u64 v[36:37], v[24:25], 2, s[10:11]
	v_add_u32_e32 v24, 0x800, v10
	v_ashrrev_i32_e32 v25, 31, v24
	v_lshl_add_u64 v[38:39], v[24:25], 2, s[10:11]
	v_add_u32_e32 v24, 0xa00, v10
	v_ashrrev_i32_e32 v25, 31, v24
	v_lshl_add_u64 v[40:41], v[24:25], 2, s[10:11]
	v_add_u32_e32 v24, 0xc00, v10
	v_ashrrev_i32_e32 v25, 31, v24
	v_ashrrev_i32_e32 v11, 31, v10
	v_lshl_add_u64 v[42:43], v[24:25], 2, s[10:11]
	v_add_u32_e32 v24, 0xe00, v10
	v_lshl_add_u64 v[30:31], v[10:11], 2, s[10:11]
	v_ashrrev_i32_e32 v25, 31, v24
	v_lshl_add_u64 v[44:45], v[24:25], 2, s[10:11]
	global_load_dword v2, v[30:31], off
	global_load_dword v11, v[32:33], off
	global_load_dword v23, v[34:35], off
	global_load_dword v24, v[36:37], off
	global_load_dword v25, v[38:39], off
	global_load_dword v26, v[40:41], off
	global_load_dword v27, v[42:43], off
	global_load_dword v28, v[44:45], off
	v_add_u32_e32 v30, 0x1000, v10
	v_ashrrev_i32_e32 v31, 31, v30
	v_add_u32_e32 v32, 0x1200, v10
	v_add_u32_e32 v34, 0x1400, v10
	v_add_u32_e32 v36, 0x1600, v10
	v_add_u32_e32 v38, 0x1800, v10
	v_add_u32_e32 v40, 0x1a00, v10
	v_add_u32_e32 v42, 0x1c00, v10
	v_add_u32_e32 v44, 0x1e00, v10
	v_lshl_add_u64 v[30:31], v[30:31], 2, s[10:11]
	v_ashrrev_i32_e32 v33, 31, v32
	v_ashrrev_i32_e32 v35, 31, v34
	v_ashrrev_i32_e32 v37, 31, v36
	v_ashrrev_i32_e32 v39, 31, v38
	v_ashrrev_i32_e32 v41, 31, v40
	v_ashrrev_i32_e32 v43, 31, v42
	v_ashrrev_i32_e32 v45, 31, v44
	v_lshl_add_u64 v[32:33], v[32:33], 2, s[10:11]
	v_lshl_add_u64 v[34:35], v[34:35], 2, s[10:11]
	v_lshl_add_u64 v[36:37], v[36:37], 2, s[10:11]
	v_lshl_add_u64 v[38:39], v[38:39], 2, s[10:11]
	v_lshl_add_u64 v[40:41], v[40:41], 2, s[10:11]
	v_lshl_add_u64 v[42:43], v[42:43], 2, s[10:11]
	v_lshl_add_u64 v[44:45], v[44:45], 2, s[10:11]
	global_load_dword v29, v[30:31], off
	global_load_dword v46, v[32:33], off
	global_load_dword v47, v[34:35], off
	global_load_dword v48, v[36:37], off
	global_load_dword v49, v[38:39], off
	global_load_dword v50, v[40:41], off
	global_load_dword v51, v[42:43], off
	global_load_dword v52, v[44:45], off
	v_add_u32_e32 v30, 0x2000, v10
	v_ashrrev_i32_e32 v31, 31, v30
	v_add_u32_e32 v32, 0x2200, v10
	v_add_u32_e32 v34, 0x2400, v10
	v_add_u32_e32 v36, 0x2600, v10
	v_add_u32_e32 v38, 0x2800, v10
	v_add_u32_e32 v40, 0x2a00, v10
	v_add_u32_e32 v42, 0x2c00, v10
	v_add_u32_e32 v44, 0x2e00, v10
	v_lshl_add_u64 v[30:31], v[30:31], 2, s[10:11]
	v_ashrrev_i32_e32 v33, 31, v32
	v_ashrrev_i32_e32 v35, 31, v34
; __device__ __forceinline__ void phase3(const Args& a, LAS unsigned char* lds) {
;     ...
;         if (tid < 256) { float t = 0.f;
; #pragma unroll
;             for (int kch = 0; kch < 64; ++kch) t += c1p[kch * 512 + kv * 256 + tid];
;             c1s[tid] = t; }
	v_ashrrev_i32_e32 v37, 31, v36
	v_ashrrev_i32_e32 v39, 31, v38
	v_ashrrev_i32_e32 v41, 31, v40
	v_ashrrev_i32_e32 v43, 31, v42
	v_ashrrev_i32_e32 v45, 31, v44
	v_lshl_add_u64 v[32:33], v[32:33], 2, s[10:11]
	v_lshl_add_u64 v[34:35], v[34:35], 2, s[10:11]
	v_lshl_add_u64 v[36:37], v[36:37], 2, s[10:11]
	v_lshl_add_u64 v[38:39], v[38:39], 2, s[10:11]
	v_lshl_add_u64 v[40:41], v[40:41], 2, s[10:11]
	v_lshl_add_u64 v[42:43], v[42:43], 2, s[10:11]
	v_lshl_add_u64 v[44:45], v[44:45], 2, s[10:11]
	global_load_dword v53, v[30:31], off
	global_load_dword v54, v[32:33], off
	global_load_dword v55, v[34:35], off
	global_load_dword v56, v[36:37], off
	global_load_dword v57, v[38:39], off
	global_load_dword v58, v[40:41], off
	global_load_dword v59, v[42:43], off
	global_load_dword v60, v[44:45], off
	v_add_u32_e32 v30, 0x3000, v10
	v_ashrrev_i32_e32 v31, 31, v30
	v_add_u32_e32 v32, 0x3200, v10
	v_add_u32_e32 v34, 0x3400, v10
	v_add_u32_e32 v36, 0x3600, v10
	v_add_u32_e32 v38, 0x3800, v10
	v_add_u32_e32 v40, 0x3a00, v10
	v_add_u32_e32 v42, 0x3c00, v10
	v_add_u32_e32 v44, 0x3e00, v10
	v_lshl_add_u64 v[30:31], v[30:31], 2, s[10:11]
	v_ashrrev_i32_e32 v33, 31, v32
	v_ashrrev_i32_e32 v35, 31, v34
	v_ashrrev_i32_e32 v37, 31, v36
	v_ashrrev_i32_e32 v39, 31, v38
	v_ashrrev_i32_e32 v41, 31, v40
	v_ashrrev_i32_e32 v43, 31, v42
	v_ashrrev_i32_e32 v45, 31, v44
	v_lshl_add_u64 v[32:33], v[32:33], 2, s[10:11]
	v_lshl_add_u64 v[34:35], v[34:35], 2, s[10:11]
	v_lshl_add_u64 v[36:37], v[36:37], 2, s[10:11]
	v_lshl_add_u64 v[38:39], v[38:39], 2, s[10:11]
	v_lshl_add_u64 v[40:41], v[40:41], 2, s[10:11]
	v_lshl_add_u64 v[42:43], v[42:43], 2, s[10:11]
	v_lshl_add_u64 v[44:45], v[44:45], 2, s[10:11]
	global_load_dword v61, v[30:31], off
	global_load_dword v62, v[32:33], off
	global_load_dword v63, v[34:35], off
	global_load_dword v64, v[36:37], off
	global_load_dword v65, v[38:39], off
	global_load_dword v66, v[40:41], off
	global_load_dword v67, v[42:43], off
	global_load_dword v68, v[44:45], off
	v_add_u32_e32 v30, 0x4000, v10
	v_ashrrev_i32_e32 v31, 31, v30
	v_add_u32_e32 v32, 0x4200, v10
	v_add_u32_e32 v34, 0x4400, v10
	v_add_u32_e32 v36, 0x4600, v10
	v_add_u32_e32 v38, 0x4800, v10
	v_add_u32_e32 v40, 0x4a00, v10
	v_add_u32_e32 v42, 0x4c00, v10
	v_add_u32_e32 v44, 0x4e00, v10
	v_lshl_add_u64 v[30:31], v[30:31], 2, s[10:11]
	v_ashrrev_i32_e32 v33, 31, v32
	v_ashrrev_i32_e32 v35, 31, v34
	v_ashrrev_i32_e32 v37, 31, v36
	v_ashrrev_i32_e32 v39, 31, v38
	v_ashrrev_i32_e32 v41, 31, v40
	v_ashrrev_i32_e32 v43, 31, v42
	v_ashrrev_i32_e32 v45, 31, v44
	v_lshl_add_u64 v[32:33], v[32:33], 2, s[10:11]
	v_lshl_add_u64 v[34:35], v[34:35], 2, s[10:11]
	v_lshl_add_u64 v[36:37], v[36:37], 2, s[10:11]
	v_lshl_add_u64 v[38:39], v[38:39], 2, s[10:11]
	v_lshl_add_u64 v[40:41], v[40:41], 2, s[10:11]
	v_lshl_add_u64 v[42:43], v[42:43], 2, s[10:11]
	v_lshl_add_u64 v[44:45], v[44:45], 2, s[10:11]
	global_load_dword v69, v[30:31], off
	global_load_dword v70, v[32:33], off
	global_load_dword v71, v[34:35], off
	global_load_dword v72, v[36:37], off
	global_load_dword v73, v[38:39], off
	global_load_dword v74, v[40:41], off
	global_load_dword v75, v[42:43], off
	global_load_dword v76, v[44:45], off
	v_add_u32_e32 v30, 0x5000, v10
	v_ashrrev_i32_e32 v31, 31, v30
	v_add_u32_e32 v32, 0x5200, v10
	v_add_u32_e32 v34, 0x5400, v10
	v_add_u32_e32 v36, 0x5600, v10
	v_add_u32_e32 v38, 0x5800, v10
	v_add_u32_e32 v40, 0x5a00, v10
	v_add_u32_e32 v42, 0x5c00, v10
	v_add_u32_e32 v44, 0x5e00, v10
	v_lshl_add_u64 v[30:31], v[30:31], 2, s[10:11]
	v_ashrrev_i32_e32 v33, 31, v32
	v_ashrrev_i32_e32 v35, 31, v34
	v_ashrrev_i32_e32 v37, 31, v36
	v_ashrrev_i32_e32 v39, 31, v38
	v_ashrrev_i32_e32 v41, 31, v40
	v_ashrrev_i32_e32 v43, 31, v42
	v_ashrrev_i32_e32 v45, 31, v44
	v_lshl_add_u64 v[32:33], v[32:33], 2, s[10:11]
	v_lshl_add_u64 v[34:35], v[34:35], 2, s[10:11]
	v_lshl_add_u64 v[36:37], v[36:37], 2, s[10:11]
	v_lshl_add_u64 v[38:39], v[38:39], 2, s[10:11]
	v_lshl_add_u64 v[40:41], v[40:41], 2, s[10:11]
	v_lshl_add_u64 v[42:43], v[42:43], 2, s[10:11]
	v_lshl_add_u64 v[44:45], v[44:45], 2, s[10:11]
	global_load_dword v77, v[30:31], off
	global_load_dword v78, v[32:33], off
	global_load_dword v79, v[34:35], off
	global_load_dword v80, v[36:37], off
	global_load_dword v81, v[38:39], off
	global_load_dword v82, v[40:41], off
	global_load_dword v83, v[42:43], off
	global_load_dword v84, v[44:45], off
	v_add_u32_e32 v30, 0x6000, v10
	v_ashrrev_i32_e32 v31, 31, v30
	v_add_u32_e32 v32, 0x6200, v10
	v_add_u32_e32 v34, 0x6400, v10
	v_add_u32_e32 v36, 0x6600, v10
	v_add_u32_e32 v38, 0x6800, v10
	v_add_u32_e32 v40, 0x6a00, v10
	v_add_u32_e32 v42, 0x6c00, v10
	v_add_u32_e32 v44, 0x6e00, v10
	v_lshl_add_u64 v[30:31], v[30:31], 2, s[10:11]
	v_ashrrev_i32_e32 v33, 31, v32
	v_ashrrev_i32_e32 v35, 31, v34
	v_ashrrev_i32_e32 v37, 31, v36
	v_ashrrev_i32_e32 v39, 31, v38
	v_ashrrev_i32_e32 v41, 31, v40
	v_ashrrev_i32_e32 v43, 31, v42
	v_ashrrev_i32_e32 v45, 31, v44
	v_lshl_add_u64 v[32:33], v[32:33], 2, s[10:11]
	v_lshl_add_u64 v[34:35], v[34:35], 2, s[10:11]
	v_lshl_add_u64 v[36:37], v[36:37], 2, s[10:11]
	v_lshl_add_u64 v[38:39], v[38:39], 2, s[10:11]
	v_lshl_add_u64 v[40:41], v[40:41], 2, s[10:11]
	v_lshl_add_u64 v[42:43], v[42:43], 2, s[10:11]
	v_lshl_add_u64 v[44:45], v[44:45], 2, s[10:11]
	global_load_dword v85, v[30:31], off
	global_load_dword v86, v[32:33], off
	global_load_dword v87, v[34:35], off
	global_load_dword v88, v[36:37], off
	global_load_dword v89, v[38:39], off
	global_load_dword v90, v[40:41], off
	global_load_dword v91, v[42:43], off
	global_load_dword v92, v[44:45], off
	v_add_u32_e32 v30, 0x7000, v10
	v_ashrrev_i32_e32 v31, 31, v30
	v_add_u32_e32 v32, 0x7200, v10
	v_add_u32_e32 v34, 0x7400, v10
	v_add_u32_e32 v36, 0x7600, v10
	v_add_u32_e32 v38, 0x7800, v10
	v_add_u32_e32 v40, 0x7a00, v10
	v_add_u32_e32 v42, 0x7c00, v10
	v_add_u32_e32 v44, 0x7e00, v10
	v_lshl_add_u64 v[30:31], v[30:31], 2, s[10:11]
	v_ashrrev_i32_e32 v33, 31, v32
	v_ashrrev_i32_e32 v35, 31, v34
	v_ashrrev_i32_e32 v37, 31, v36
	v_ashrrev_i32_e32 v39, 31, v38
	v_ashrrev_i32_e32 v41, 31, v40
	v_ashrrev_i32_e32 v43, 31, v42
	v_ashrrev_i32_e32 v45, 31, v44
	v_lshl_add_u64 v[32:33], v[32:33], 2, s[10:11]
	v_lshl_add_u64 v[34:35], v[34:35], 2, s[10:11]
	v_lshl_add_u64 v[36:37], v[36:37], 2, s[10:11]
	v_lshl_add_u64 v[38:39], v[38:39], 2, s[10:11]
	v_lshl_add_u64 v[40:41], v[40:41], 2, s[10:11]
	v_lshl_add_u64 v[42:43], v[42:43], 2, s[10:11]
	v_lshl_add_u64 v[44:45], v[44:45], 2, s[10:11]
	global_load_dword v10, v[30:31], off
	global_load_dword v93, v[32:33], off
	global_load_dword v94, v[34:35], off
	global_load_dword v95, v[36:37], off
	global_load_dword v96, v[38:39], off
	global_load_dword v97, v[40:41], off
	global_load_dword v98, v[42:43], off
	global_load_dword v99, v[44:45], off
	s_waitcnt vmcnt(62)
; __device__ __forceinline__ void phase3(const Args& a, LAS unsigned char* lds) {
;     ...
;         if (tid < 256) { float t = 0.f;
; #pragma unroll
;             for (int kch = 0; kch < 64; ++kch) t += c1p[kch * 512 + kv * 256 + tid];
;             c1s[tid] = t; }
	v_add_f32_e32 v2, 0, v2
	v_add_f32_e32 v2, v2, v11
	s_waitcnt vmcnt(61)
	v_add_f32_e32 v2, v2, v23
	s_waitcnt vmcnt(60)
	v_add_f32_e32 v2, v2, v24
	s_waitcnt vmcnt(59)
	v_add_f32_e32 v2, v2, v25
	s_waitcnt vmcnt(58)
	v_add_f32_e32 v2, v2, v26
	s_waitcnt vmcnt(57)
	v_add_f32_e32 v2, v2, v27
	s_waitcnt vmcnt(56)
	v_add_f32_e32 v2, v2, v28
	s_waitcnt vmcnt(55)
	v_add_f32_e32 v2, v2, v29
	s_waitcnt vmcnt(54)
	v_add_f32_e32 v2, v2, v46
	s_waitcnt vmcnt(53)
	v_add_f32_e32 v2, v2, v47
	s_waitcnt vmcnt(52)
	v_add_f32_e32 v2, v2, v48
	s_waitcnt vmcnt(51)
	v_add_f32_e32 v2, v2, v49
	s_waitcnt vmcnt(50)
	v_add_f32_e32 v2, v2, v50
	s_waitcnt vmcnt(49)
	v_add_f32_e32 v2, v2, v51
	s_waitcnt vmcnt(48)
	v_add_f32_e32 v2, v2, v52
	s_waitcnt vmcnt(47)
	v_add_f32_e32 v2, v2, v53
	s_waitcnt vmcnt(46)
	v_add_f32_e32 v2, v2, v54
	s_waitcnt vmcnt(45)
	v_add_f32_e32 v2, v2, v55
	s_waitcnt vmcnt(44)
	v_add_f32_e32 v2, v2, v56
	s_waitcnt vmcnt(43)
	v_add_f32_e32 v2, v2, v57
	s_waitcnt vmcnt(42)
	v_add_f32_e32 v2, v2, v58
	s_waitcnt vmcnt(41)
	v_add_f32_e32 v2, v2, v59
	s_waitcnt vmcnt(40)
	v_add_f32_e32 v2, v2, v60
	s_waitcnt vmcnt(39)
	v_add_f32_e32 v2, v2, v61
	s_waitcnt vmcnt(38)
	v_add_f32_e32 v2, v2, v62
	s_waitcnt vmcnt(37)
	v_add_f32_e32 v2, v2, v63
	s_waitcnt vmcnt(36)
	v_add_f32_e32 v2, v2, v64
	s_waitcnt vmcnt(35)
	v_add_f32_e32 v2, v2, v65
	s_waitcnt vmcnt(34)
	v_add_f32_e32 v2, v2, v66
	s_waitcnt vmcnt(33)
	v_add_f32_e32 v2, v2, v67
	s_waitcnt vmcnt(32)
	v_add_f32_e32 v2, v2, v68
	s_waitcnt vmcnt(31)
	v_add_f32_e32 v2, v2, v69
	s_waitcnt vmcnt(30)
	v_add_f32_e32 v2, v2, v70
	s_waitcnt vmcnt(29)
	v_add_f32_e32 v2, v2, v71
	s_waitcnt vmcnt(28)
	v_add_f32_e32 v2, v2, v72
	s_waitcnt vmcnt(27)
	v_add_f32_e32 v2, v2, v73
	s_waitcnt vmcnt(26)
	v_add_f32_e32 v2, v2, v74
	s_waitcnt vmcnt(25)
	v_add_f32_e32 v2, v2, v75
	s_waitcnt vmcnt(24)
	v_add_f32_e32 v2, v2, v76
	s_waitcnt vmcnt(23)
	v_add_f32_e32 v2, v2, v77
	s_waitcnt vmcnt(22)
	v_add_f32_e32 v2, v2, v78
	s_waitcnt vmcnt(21)
	v_add_f32_e32 v2, v2, v79
	s_waitcnt vmcnt(20)
	v_add_f32_e32 v2, v2, v80
	s_waitcnt vmcnt(19)
	v_add_f32_e32 v2, v2, v81
	s_waitcnt vmcnt(18)
	v_add_f32_e32 v2, v2, v82
	s_waitcnt vmcnt(17)
	v_add_f32_e32 v2, v2, v83
	s_waitcnt vmcnt(16)
	v_add_f32_e32 v2, v2, v84
	s_waitcnt vmcnt(15)
	v_add_f32_e32 v2, v2, v85
	s_waitcnt vmcnt(14)
	v_add_f32_e32 v2, v2, v86
	s_waitcnt vmcnt(13)
	v_add_f32_e32 v2, v2, v87
	s_waitcnt vmcnt(12)
	v_add_f32_e32 v2, v2, v88
	s_waitcnt vmcnt(11)
	v_add_f32_e32 v2, v2, v89
	s_waitcnt vmcnt(10)
	v_add_f32_e32 v2, v2, v90
	s_waitcnt vmcnt(9)
	v_add_f32_e32 v2, v2, v91
	s_waitcnt vmcnt(8)
	v_add_f32_e32 v2, v2, v92
	s_waitcnt vmcnt(7)
	v_add_f32_e32 v2, v2, v10
	s_waitcnt vmcnt(6)
	v_add_f32_e32 v2, v2, v93
	s_waitcnt vmcnt(5)
	v_add_f32_e32 v2, v2, v94
	s_waitcnt vmcnt(4)
	v_add_f32_e32 v2, v2, v95
	s_waitcnt vmcnt(3)
	v_add_f32_e32 v2, v2, v96
	s_waitcnt vmcnt(2)
	v_add_f32_e32 v2, v2, v97
	s_waitcnt vmcnt(1)
	v_add_f32_e32 v2, v2, v98
	s_waitcnt vmcnt(0)
	v_add_f32_e32 v2, v2, v99
	ds_write_b32 v12, v2
